# v19 + attention O tile stored through a wave-private LDS transpose (8 coalesced dwordx4 stores)
# speedup vs baseline: 1.0147x; 1.0147x over previous
; DI unsigned pack2(float a, float b) { f2_t v = {a, b}; bf2_t r = __builtin_convertvector(v, bf2_t); return __builtin_bit_cast(unsigned, r); }
; DI float bf_lo(unsigned u) { return __uint_as_float(u << 16); }
; DI float bf_hi(unsigned u) { return __uint_as_float(u & 0xffff0000u); }
; template <int PM> DI void attn_phase(const Params& p, int l, char* smem, int* s_item, int wv, int cidx) {
;     ...
;       {
;         const char* gl = gate_s + (w * 32 + l31) * 264 + 8 * h;
;         u16* op = p.O + (size_t)Rq * DM + mixer * 512 + head * 128 + 4 * h;
;         const float* sg = sg_s + 4 * h;
; #pragma unroll
;         for (int db = 0; db < 4; ++db)
; #pragma unroll
;           for (int g = 0; g < 4; ++g) {
;             const int d = db * 32 + 8 * g;
;             f32x4 sv = {1.f, 1.f, 1.f, 1.f};
;             if (mixer == 0) sv = *(const f32x4*)(sg + d);
;             const u32x2 gv = *(const u32x2*)(gl + d * 2);
;             u32x2 o;
;             o[0] = pack2(ov[db][4 * g + 0] * rr * sv[0] * bf_lo(gv[0]), ov[db][4 * g + 1] * rr * sv[1] * bf_hi(gv[0]));
;             o[1] = pack2(ov[db][4 * g + 2] * rr * sv[2] * bf_lo(gv[1]), ov[db][4 * g + 3] * rr * sv[3] * bf_hi(gv[1]));
;             *(u32x2*)(op + d) = o;
;           }
.LBB0_527:
	v_readlane_b32 s0, v253, 37
	v_mul_u32_u24_e32 v208, 0x110, v240
	v_lshl_add_u32 v208, v198, 1, v208
	s_mulk_i32 s0, 0x2200
	v_add_u32_e32 v208, s0, v208
	ds_read_b64 v[16:17], v252
	ds_read_b64 v[18:19], v252 offset:16
	ds_read_b64 v[20:21], v252 offset:32
	ds_read_b64 v[22:23], v252 offset:48
	ds_read_b64 v[24:25], v252 offset:64
	ds_read_b64 v[26:27], v252 offset:80
	ds_read_b64 v[28:29], v252 offset:96
	ds_read_b64 v[30:31], v252 offset:112
	ds_read_b64 v[32:33], v252 offset:128
	ds_read_b64 v[34:35], v252 offset:144
	ds_read_b64 v[36:37], v252 offset:160
	ds_read_b64 v[38:39], v252 offset:176
	ds_read_b64 v[40:41], v252 offset:192
	ds_read_b64 v[42:43], v252 offset:208
	ds_read_b64 v[44:45], v252 offset:224
	ds_read_b64 v[46:47], v252 offset:240
	s_and_b64 vcc, exec, s[72:73]
	v_mov_b32_e32 v93, 1.0
	v_mov_b32_e32 v94, 1.0
	v_mov_b32_e32 v95, 1.0
	s_cbranch_vccnz .LBB0_529
	ds_read_b128 v[92:95], v245
.LBB0_529:
	s_waitcnt lgkmcnt(0)
	v_mov_b64_e32 v[172:173], v[16:17]
	v_pk_mul_f32 v[106:107], v[106:107], v[170:171] op_sel_hi:[1,0]
	v_pk_mul_f32 v[104:105], v[104:105], v[170:171] op_sel_hi:[1,0]
	s_waitcnt lgkmcnt(0)
	v_pk_mul_f32 v[92:93], v[106:107], v[92:93]
	v_pk_mul_f32 v[94:95], v[104:105], v[94:95]
	s_waitcnt lgkmcnt(0)
	v_lshlrev_b32_e32 v106, 16, v172
	v_and_b32_e32 v107, 0xffff0000, v172
	v_lshlrev_b32_e32 v104, 16, v173
	v_and_b32_e32 v105, 0xffff0000, v173
	v_pk_mul_f32 v[92:93], v[92:93], v[106:107]
	v_pk_mul_f32 v[94:95], v[94:95], v[104:105]
	v_cvt_pk_bf16_f32 v92, v92, v93
	v_cvt_pk_bf16_f32 v93, v94, v95
	ds_write_b64 v208, v[92:93]
	v_mov_b32_e32 v92, 1.0
	s_and_b64 vcc, exec, s[72:73]
	v_mov_b32_e32 v104, 1.0
	v_mov_b32_e32 v105, 1.0
	v_mov_b32_e32 v106, 1.0
	v_mov_b32_e32 v107, 1.0
	s_cbranch_vccnz .LBB0_531
	ds_read_b128 v[104:107], v245 offset:32
.LBB0_531:
	v_mov_b64_e32 v[94:95], v[18:19]
	v_mov_b32_e32 v171, v170
	v_pk_mul_f32 v[112:113], v[112:113], v[170:171]
	s_and_b64 vcc, exec, s[72:73]
	s_waitcnt lgkmcnt(0)
	v_pk_mul_f32 v[104:105], v[112:113], v[104:105]
	s_waitcnt lgkmcnt(0)
	v_lshlrev_b32_e32 v112, 16, v94
	v_and_b32_e32 v113, 0xffff0000, v94
	v_pk_mul_f32 v[104:105], v[104:105], v[112:113]
	v_mov_b32_e32 v93, 1.0
	v_cvt_pk_bf16_f32 v94, v104, v105
	v_pk_mul_f32 v[104:105], v[108:109], v[170:171]
	s_nop 0
	v_pk_mul_f32 v[104:105], v[104:105], v[106:107]
	v_lshlrev_b32_e32 v106, 16, v95
	v_and_b32_e32 v107, 0xffff0000, v95
	v_pk_mul_f32 v[104:105], v[104:105], v[106:107]
	s_nop 0
	v_cvt_pk_bf16_f32 v95, v104, v105
	ds_write_b64 v208, v[94:95] offset:16
	v_mov_b32_e32 v94, 1.0
	v_mov_b32_e32 v95, 1.0
	s_cbranch_vccnz .LBB0_533
	ds_read_b128 v[92:95], v245 offset:64
.LBB0_533:
	v_mov_b64_e32 v[104:105], v[20:21]
	v_pk_mul_f32 v[106:107], v[110:111], v[170:171]
	v_pk_mul_f32 v[14:15], v[14:15], v[170:171]
	s_waitcnt lgkmcnt(0)
	v_pk_mul_f32 v[92:93], v[106:107], v[92:93]
	v_pk_mul_f32 v[14:15], v[14:15], v[94:95]
	s_waitcnt lgkmcnt(0)
	v_lshlrev_b32_e32 v106, 16, v104
	v_and_b32_e32 v107, 0xffff0000, v104
	v_lshlrev_b32_e32 v94, 16, v105
	v_and_b32_e32 v95, 0xffff0000, v105
	v_pk_mul_f32 v[92:93], v[92:93], v[106:107]
	v_pk_mul_f32 v[14:15], v[14:15], v[94:95]
	v_cvt_pk_bf16_f32 v92, v92, v93
	v_cvt_pk_bf16_f32 v93, v14, v15
	ds_write_b64 v208, v[92:93] offset:32
	v_mov_b32_e32 v92, 1.0
	s_and_b64 vcc, exec, s[72:73]
	v_mov_b32_e32 v104, 1.0
	v_mov_b32_e32 v105, 1.0
	v_mov_b32_e32 v106, 1.0
	v_mov_b32_e32 v107, 1.0
	s_cbranch_vccnz .LBB0_535
	ds_read_b128 v[104:107], v245 offset:96
.LBB0_535:
	v_mov_b64_e32 v[14:15], v[22:23]
	v_pk_mul_f32 v[94:95], v[114:115], v[170:171]
	v_pk_mul_f32 v[108:109], v[116:117], v[170:171]
	s_waitcnt lgkmcnt(0)
	v_pk_mul_f32 v[94:95], v[94:95], v[104:105]
	s_and_b64 vcc, exec, s[72:73]
	s_waitcnt lgkmcnt(0)
	v_lshlrev_b32_e32 v104, 16, v14
	v_and_b32_e32 v105, 0xffff0000, v14
	v_pk_mul_f32 v[94:95], v[94:95], v[104:105]
	v_lshlrev_b32_e32 v104, 16, v15
	v_cvt_pk_bf16_f32 v14, v94, v95
	v_pk_mul_f32 v[94:95], v[108:109], v[106:107]
	v_and_b32_e32 v105, 0xffff0000, v15
	v_pk_mul_f32 v[94:95], v[94:95], v[104:105]
	v_mov_b32_e32 v93, 1.0
	v_cvt_pk_bf16_f32 v15, v94, v95
	v_mov_b32_e32 v94, 1.0
	v_mov_b32_e32 v95, 1.0
	ds_write_b64 v208, v[14:15] offset:48
	s_cbranch_vccnz .LBB0_537
	ds_read_b128 v[92:95], v245 offset:128
.LBB0_537:
	v_mov_b64_e32 v[14:15], v[24:25]
	v_pk_mul_f32 v[104:105], v[132:133], v[170:171]
	v_pk_mul_f32 v[106:107], v[128:129], v[170:171]
	s_waitcnt lgkmcnt(0)
	v_pk_mul_f32 v[92:93], v[104:105], v[92:93]
	s_and_b64 vcc, exec, s[72:73]
	s_waitcnt lgkmcnt(0)
	v_lshlrev_b32_e32 v104, 16, v14
	v_and_b32_e32 v105, 0xffff0000, v14
	v_pk_mul_f32 v[92:93], v[92:93], v[104:105]
	v_mov_b32_e32 v104, 1.0
	v_cvt_pk_bf16_f32 v14, v92, v93
	v_pk_mul_f32 v[92:93], v[106:107], v[94:95]
	v_lshlrev_b32_e32 v94, 16, v15
	v_and_b32_e32 v95, 0xffff0000, v15
	v_pk_mul_f32 v[92:93], v[92:93], v[94:95]
	v_mov_b32_e32 v105, 1.0
	v_cvt_pk_bf16_f32 v15, v92, v93
	v_mov_b32_e32 v92, 1.0
	v_mov_b32_e32 v106, 1.0
	v_mov_b32_e32 v107, 1.0
	ds_write_b64 v208, v[14:15] offset:64
	s_cbranch_vccnz .LBB0_539
	ds_read_b128 v[104:107], v245 offset:160
.LBB0_539:
	v_mov_b64_e32 v[14:15], v[26:27]
	v_pk_mul_f32 v[94:95], v[124:125], v[170:171]
	v_pk_mul_f32 v[108:109], v[122:123], v[170:171]
	s_waitcnt lgkmcnt(0)
	v_pk_mul_f32 v[94:95], v[94:95], v[104:105]
	s_and_b64 vcc, exec, s[72:73]
	s_waitcnt lgkmcnt(0)
	v_lshlrev_b32_e32 v104, 16, v14
	v_and_b32_e32 v105, 0xffff0000, v14
	v_pk_mul_f32 v[94:95], v[94:95], v[104:105]
	v_lshlrev_b32_e32 v104, 16, v15
	v_cvt_pk_bf16_f32 v14, v94, v95
	v_pk_mul_f32 v[94:95], v[108:109], v[106:107]
	v_and_b32_e32 v105, 0xffff0000, v15
	v_pk_mul_f32 v[94:95], v[94:95], v[104:105]
	v_mov_b32_e32 v93, 1.0
	v_cvt_pk_bf16_f32 v15, v94, v95
	v_mov_b32_e32 v94, 1.0
	v_mov_b32_e32 v95, 1.0
	ds_write_b64 v208, v[14:15] offset:80
	s_cbranch_vccnz .LBB0_541
	ds_read_b128 v[92:95], v245 offset:192
; DI unsigned pack2(float a, float b) { f2_t v = {a, b}; bf2_t r = __builtin_convertvector(v, bf2_t); return __builtin_bit_cast(unsigned, r); }
; DI float bf_lo(unsigned u) { return __uint_as_float(u << 16); }
; DI float bf_hi(unsigned u) { return __uint_as_float(u & 0xffff0000u); }
; template <int PM> DI void attn_phase(const Params& p, int l, char* smem, int* s_item, int wv, int cidx) {
;     ...
;         for (int db = 0; db < 4; ++db)
; #pragma unroll
;           for (int g = 0; g < 4; ++g) {
;             const int d = db * 32 + 8 * g;
;             f32x4 sv = {1.f, 1.f, 1.f, 1.f};
;             if (mixer == 0) sv = *(const f32x4*)(sg + d);
;             const u32x2 gv = *(const u32x2*)(gl + d * 2);
;             u32x2 o;
;             o[0] = pack2(ov[db][4 * g + 0] * rr * sv[0] * bf_lo(gv[0]), ov[db][4 * g + 1] * rr * sv[1] * bf_hi(gv[0]));
;             o[1] = pack2(ov[db][4 * g + 2] * rr * sv[2] * bf_lo(gv[1]), ov[db][4 * g + 3] * rr * sv[3] * bf_hi(gv[1]));
;             *(u32x2*)(op + d) = o;
.LBB0_541:
	v_mov_b64_e32 v[14:15], v[28:29]
	v_pk_mul_f32 v[104:105], v[120:121], v[170:171]
	v_pk_mul_f32 v[106:107], v[118:119], v[170:171]
	s_waitcnt lgkmcnt(0)
	v_pk_mul_f32 v[92:93], v[104:105], v[92:93]
	s_and_b64 vcc, exec, s[72:73]
	s_waitcnt lgkmcnt(0)
	v_lshlrev_b32_e32 v104, 16, v14
	v_and_b32_e32 v105, 0xffff0000, v14
	v_pk_mul_f32 v[92:93], v[92:93], v[104:105]
	v_mov_b32_e32 v104, 1.0
	v_cvt_pk_bf16_f32 v14, v92, v93
	v_pk_mul_f32 v[92:93], v[106:107], v[94:95]
	v_lshlrev_b32_e32 v94, 16, v15
	v_and_b32_e32 v95, 0xffff0000, v15
	v_pk_mul_f32 v[92:93], v[92:93], v[94:95]
	v_mov_b32_e32 v105, 1.0
	v_cvt_pk_bf16_f32 v15, v92, v93
	v_mov_b32_e32 v92, 1.0
	v_mov_b32_e32 v106, 1.0
	v_mov_b32_e32 v107, 1.0
	ds_write_b64 v208, v[14:15] offset:96
	s_cbranch_vccnz .LBB0_543
	ds_read_b128 v[104:107], v245 offset:224
.LBB0_543:
	v_mov_b64_e32 v[14:15], v[30:31]
	v_pk_mul_f32 v[94:95], v[126:127], v[170:171]
	v_pk_mul_f32 v[108:109], v[130:131], v[170:171]
	s_waitcnt lgkmcnt(0)
	v_pk_mul_f32 v[94:95], v[94:95], v[104:105]
	s_and_b64 vcc, exec, s[72:73]
	s_waitcnt lgkmcnt(0)
	v_lshlrev_b32_e32 v104, 16, v14
	v_and_b32_e32 v105, 0xffff0000, v14
	v_pk_mul_f32 v[94:95], v[94:95], v[104:105]
	v_lshlrev_b32_e32 v104, 16, v15
	v_cvt_pk_bf16_f32 v14, v94, v95
	v_pk_mul_f32 v[94:95], v[108:109], v[106:107]
	v_and_b32_e32 v105, 0xffff0000, v15
	v_pk_mul_f32 v[94:95], v[94:95], v[104:105]
	v_mov_b32_e32 v93, 1.0
	v_cvt_pk_bf16_f32 v15, v94, v95
	v_mov_b32_e32 v94, 1.0
	v_mov_b32_e32 v95, 1.0
	ds_write_b64 v208, v[14:15] offset:112
	s_cbranch_vccnz .LBB0_545
	ds_read_b128 v[92:95], v245 offset:256
.LBB0_545:
	v_mov_b64_e32 v[14:15], v[32:33]
	v_pk_mul_f32 v[104:105], v[152:153], v[170:171]
	v_pk_mul_f32 v[106:107], v[148:149], v[170:171]
	s_waitcnt lgkmcnt(0)
	v_pk_mul_f32 v[92:93], v[104:105], v[92:93]
	s_and_b64 vcc, exec, s[72:73]
	s_waitcnt lgkmcnt(0)
	v_lshlrev_b32_e32 v104, 16, v14
	v_and_b32_e32 v105, 0xffff0000, v14
	v_pk_mul_f32 v[92:93], v[92:93], v[104:105]
	v_mov_b32_e32 v104, 1.0
	v_cvt_pk_bf16_f32 v14, v92, v93
	v_pk_mul_f32 v[92:93], v[106:107], v[94:95]
	v_lshlrev_b32_e32 v94, 16, v15
	v_and_b32_e32 v95, 0xffff0000, v15
	v_pk_mul_f32 v[92:93], v[92:93], v[94:95]
	v_mov_b32_e32 v105, 1.0
	v_cvt_pk_bf16_f32 v15, v92, v93
	v_mov_b32_e32 v92, 1.0
	v_mov_b32_e32 v106, 1.0
	v_mov_b32_e32 v107, 1.0
	ds_write_b64 v208, v[14:15] offset:128
	s_cbranch_vccnz .LBB0_547
	ds_read_b128 v[104:107], v245 offset:288
.LBB0_547:
	v_mov_b64_e32 v[14:15], v[34:35]
	v_pk_mul_f32 v[94:95], v[140:141], v[170:171]
	v_pk_mul_f32 v[108:109], v[138:139], v[170:171]
	s_waitcnt lgkmcnt(0)
	v_pk_mul_f32 v[94:95], v[94:95], v[104:105]
	s_and_b64 vcc, exec, s[72:73]
	s_waitcnt lgkmcnt(0)
	v_lshlrev_b32_e32 v104, 16, v14
	v_and_b32_e32 v105, 0xffff0000, v14
	v_pk_mul_f32 v[94:95], v[94:95], v[104:105]
	v_lshlrev_b32_e32 v104, 16, v15
	v_cvt_pk_bf16_f32 v14, v94, v95
	v_pk_mul_f32 v[94:95], v[108:109], v[106:107]
	v_and_b32_e32 v105, 0xffff0000, v15
	v_pk_mul_f32 v[94:95], v[94:95], v[104:105]
	v_mov_b32_e32 v93, 1.0
	v_cvt_pk_bf16_f32 v15, v94, v95
	v_mov_b32_e32 v94, 1.0
	v_mov_b32_e32 v95, 1.0
	ds_write_b64 v208, v[14:15] offset:144
	s_cbranch_vccnz .LBB0_549
	ds_read_b128 v[92:95], v245 offset:320
.LBB0_549:
	v_mov_b64_e32 v[14:15], v[36:37]
	v_pk_mul_f32 v[104:105], v[136:137], v[170:171]
	v_pk_mul_f32 v[106:107], v[134:135], v[170:171]
	s_waitcnt lgkmcnt(0)
	v_pk_mul_f32 v[92:93], v[104:105], v[92:93]
	s_and_b64 vcc, exec, s[72:73]
	s_waitcnt lgkmcnt(0)
	v_lshlrev_b32_e32 v104, 16, v14
	v_and_b32_e32 v105, 0xffff0000, v14
	v_pk_mul_f32 v[92:93], v[92:93], v[104:105]
	v_mov_b32_e32 v104, 1.0
	v_cvt_pk_bf16_f32 v14, v92, v93
	v_pk_mul_f32 v[92:93], v[106:107], v[94:95]
	v_lshlrev_b32_e32 v94, 16, v15
	v_and_b32_e32 v95, 0xffff0000, v15
	v_pk_mul_f32 v[92:93], v[92:93], v[94:95]
	v_mov_b32_e32 v105, 1.0
	v_cvt_pk_bf16_f32 v15, v92, v93
	v_mov_b32_e32 v92, 1.0
	v_mov_b32_e32 v106, 1.0
	v_mov_b32_e32 v107, 1.0
	ds_write_b64 v208, v[14:15] offset:160
	s_cbranch_vccnz .LBB0_551
	ds_read_b128 v[104:107], v245 offset:352
.LBB0_551:
	v_mov_b64_e32 v[14:15], v[38:39]
	v_pk_mul_f32 v[94:95], v[142:143], v[170:171]
	v_pk_mul_f32 v[108:109], v[150:151], v[170:171]
	s_waitcnt lgkmcnt(0)
	v_pk_mul_f32 v[94:95], v[94:95], v[104:105]
	s_and_b64 vcc, exec, s[72:73]
	s_waitcnt lgkmcnt(0)
	v_lshlrev_b32_e32 v104, 16, v14
	v_and_b32_e32 v105, 0xffff0000, v14
	v_pk_mul_f32 v[94:95], v[94:95], v[104:105]
	v_lshlrev_b32_e32 v104, 16, v15
	v_cvt_pk_bf16_f32 v14, v94, v95
	v_pk_mul_f32 v[94:95], v[108:109], v[106:107]
	v_and_b32_e32 v105, 0xffff0000, v15
	v_pk_mul_f32 v[94:95], v[94:95], v[104:105]
	v_mov_b32_e32 v93, 1.0
	v_cvt_pk_bf16_f32 v15, v94, v95
	v_mov_b32_e32 v94, 1.0
	v_mov_b32_e32 v95, 1.0
	ds_write_b64 v208, v[14:15] offset:176
	s_cbranch_vccnz .LBB0_553
	ds_read_b128 v[92:95], v245 offset:384
; DI unsigned pack2(float a, float b) { f2_t v = {a, b}; bf2_t r = __builtin_convertvector(v, bf2_t); return __builtin_bit_cast(unsigned, r); }
; DI float bf_lo(unsigned u) { return __uint_as_float(u << 16); }
; DI float bf_hi(unsigned u) { return __uint_as_float(u & 0xffff0000u); }
; template <int PM> DI void attn_phase(const Params& p, int l, char* smem, int* s_item, int wv, int cidx) {
;     ...
;         for (int db = 0; db < 4; ++db)
; #pragma unroll
;           for (int g = 0; g < 4; ++g) {
;             const int d = db * 32 + 8 * g;
;             f32x4 sv = {1.f, 1.f, 1.f, 1.f};
;             if (mixer == 0) sv = *(const f32x4*)(sg + d);
;             const u32x2 gv = *(const u32x2*)(gl + d * 2);
;             u32x2 o;
;             o[0] = pack2(ov[db][4 * g + 0] * rr * sv[0] * bf_lo(gv[0]), ov[db][4 * g + 1] * rr * sv[1] * bf_hi(gv[0]));
;             o[1] = pack2(ov[db][4 * g + 2] * rr * sv[2] * bf_lo(gv[1]), ov[db][4 * g + 3] * rr * sv[3] * bf_hi(gv[1]));
;             *(u32x2*)(op + d) = o;
;           }
.LBB0_553:
	v_mov_b64_e32 v[14:15], v[40:41]
	v_pk_mul_f32 v[104:105], v[168:169], v[170:171]
	v_pk_mul_f32 v[106:107], v[164:165], v[170:171]
	s_waitcnt lgkmcnt(0)
	v_pk_mul_f32 v[92:93], v[104:105], v[92:93]
	s_and_b64 vcc, exec, s[72:73]
	s_waitcnt lgkmcnt(0)
	v_lshlrev_b32_e32 v104, 16, v14
	v_and_b32_e32 v105, 0xffff0000, v14
	v_pk_mul_f32 v[92:93], v[92:93], v[104:105]
	v_mov_b32_e32 v104, 1.0
	v_cvt_pk_bf16_f32 v14, v92, v93
	v_pk_mul_f32 v[92:93], v[106:107], v[94:95]
	v_lshlrev_b32_e32 v94, 16, v15
	v_and_b32_e32 v95, 0xffff0000, v15
	v_pk_mul_f32 v[92:93], v[92:93], v[94:95]
	v_mov_b32_e32 v105, 1.0
	v_cvt_pk_bf16_f32 v15, v92, v93
	v_mov_b32_e32 v92, 1.0
	v_mov_b32_e32 v106, 1.0
	v_mov_b32_e32 v107, 1.0
	ds_write_b64 v208, v[14:15] offset:192
	s_cbranch_vccnz .LBB0_555
	ds_read_b128 v[104:107], v245 offset:416
.LBB0_555:
	v_mov_b64_e32 v[14:15], v[42:43]
	v_pk_mul_f32 v[94:95], v[160:161], v[170:171]
	v_pk_mul_f32 v[108:109], v[158:159], v[170:171]
	s_waitcnt lgkmcnt(0)
	v_pk_mul_f32 v[94:95], v[94:95], v[104:105]
	s_and_b64 vcc, exec, s[72:73]
	s_waitcnt lgkmcnt(0)
	v_lshlrev_b32_e32 v104, 16, v14
	v_and_b32_e32 v105, 0xffff0000, v14
	v_pk_mul_f32 v[94:95], v[94:95], v[104:105]
	v_lshlrev_b32_e32 v104, 16, v15
	v_cvt_pk_bf16_f32 v14, v94, v95
	v_pk_mul_f32 v[94:95], v[108:109], v[106:107]
	v_and_b32_e32 v105, 0xffff0000, v15
	v_pk_mul_f32 v[94:95], v[94:95], v[104:105]
	v_mov_b32_e32 v93, 1.0
	v_cvt_pk_bf16_f32 v15, v94, v95
	v_mov_b32_e32 v94, 1.0
	v_mov_b32_e32 v95, 1.0
	ds_write_b64 v208, v[14:15] offset:208
	s_cbranch_vccnz .LBB0_557
	ds_read_b128 v[92:95], v245 offset:448
.LBB0_557:
	v_mov_b64_e32 v[14:15], v[44:45]
	v_pk_mul_f32 v[104:105], v[156:157], v[170:171]
	v_pk_mul_f32 v[106:107], v[154:155], v[170:171]
	s_waitcnt lgkmcnt(0)
	v_pk_mul_f32 v[92:93], v[104:105], v[92:93]
	s_and_b64 vcc, exec, s[72:73]
	s_waitcnt lgkmcnt(0)
	v_lshlrev_b32_e32 v104, 16, v14
	v_and_b32_e32 v105, 0xffff0000, v14
	v_pk_mul_f32 v[92:93], v[92:93], v[104:105]
	s_nop 0
	v_cvt_pk_bf16_f32 v14, v92, v93
	v_pk_mul_f32 v[92:93], v[106:107], v[94:95]
	v_lshlrev_b32_e32 v94, 16, v15
	v_and_b32_e32 v95, 0xffff0000, v15
	v_pk_mul_f32 v[92:93], v[92:93], v[94:95]
	v_mov_b32_e32 v94, 1.0
	v_cvt_pk_bf16_f32 v15, v92, v93
	v_mov_b32_e32 v92, 1.0
	v_mov_b32_e32 v93, 1.0
	v_mov_b32_e32 v95, 1.0
	ds_write_b64 v208, v[14:15] offset:224
	s_cbranch_vccnz .LBB0_559
	ds_read_b128 v[92:95], v245 offset:480
.LBB0_559:
	v_mov_b64_e32 v[14:15], v[46:47]
	v_pk_mul_f32 v[104:105], v[162:163], v[170:171]
	v_pk_mul_f32 v[106:107], v[166:167], v[170:171]
	s_waitcnt lgkmcnt(0)
	v_pk_mul_f32 v[92:93], v[104:105], v[92:93]
	s_waitcnt lgkmcnt(0)
	v_lshlrev_b32_e32 v104, 16, v14
	v_and_b32_e32 v105, 0xffff0000, v14
	v_pk_mul_f32 v[92:93], v[92:93], v[104:105]
	s_nop 0
	v_cvt_pk_bf16_f32 v14, v92, v93
	v_pk_mul_f32 v[92:93], v[106:107], v[94:95]
	v_lshlrev_b32_e32 v94, 16, v15
	v_and_b32_e32 v95, 0xffff0000, v15
	v_pk_mul_f32 v[92:93], v[92:93], v[94:95]
	s_nop 0
	v_cvt_pk_bf16_f32 v15, v92, v93
	ds_write_b64 v208, v[14:15] offset:240
	v_lshrrev_b32_e32 v212, 4, v240
	v_lshrrev_b32_e32 v213, 1, v198
	v_add_u32_e32 v212, v212, v213
	v_and_b32_e32 v213, 15, v240
	v_mul_u32_u24_e32 v209, 0x110, v212
	v_lshl_add_u32 v209, v213, 4, v209
	v_add_u32_e32 v209, s0, v209
	v_sub_u32_e32 v212, v212, v240
	v_lshlrev_b32_e32 v212, 12, v212
	v_lshl_add_u32 v212, v213, 4, v212
	v_lshlrev_b32_e32 v213, 1, v198
	v_sub_u32_e32 v212, v212, v213
	v_ashrrev_i32_e32 v213, 31, v212
	v_lshl_add_u64 v[210:211], v[212:213], 0, v[226:227]
	s_mov_b64 s[0:1], 0x4000
	s_waitcnt lgkmcnt(0)
	ds_read_b128 v[16:19], v209
	ds_read_b128 v[20:23], v209 offset:1088
	ds_read_b128 v[24:27], v209 offset:2176
	ds_read_b128 v[28:31], v209 offset:3264
	ds_read_b128 v[32:35], v209 offset:4352
	ds_read_b128 v[36:39], v209 offset:5440
	ds_read_b128 v[40:43], v209 offset:6528
	ds_read_b128 v[44:47], v209 offset:7616
	s_waitcnt lgkmcnt(7)
	global_store_dwordx4 v[210:211], v[16:19], off
	s_nop 1
	v_lshl_add_u64 v[210:211], v[210:211], 0, s[0:1]
	s_waitcnt lgkmcnt(6)
	global_store_dwordx4 v[210:211], v[20:23], off
	s_nop 1
	v_lshl_add_u64 v[210:211], v[210:211], 0, s[0:1]
	s_waitcnt lgkmcnt(5)
	global_store_dwordx4 v[210:211], v[24:27], off
	s_nop 1
	v_lshl_add_u64 v[210:211], v[210:211], 0, s[0:1]
	s_waitcnt lgkmcnt(4)
	global_store_dwordx4 v[210:211], v[28:31], off
	s_nop 1
	v_lshl_add_u64 v[210:211], v[210:211], 0, s[0:1]
	s_waitcnt lgkmcnt(3)
	global_store_dwordx4 v[210:211], v[32:35], off
	s_nop 1
	v_lshl_add_u64 v[210:211], v[210:211], 0, s[0:1]
	s_waitcnt lgkmcnt(2)
	global_store_dwordx4 v[210:211], v[36:39], off
	s_nop 1
	v_lshl_add_u64 v[210:211], v[210:211], 0, s[0:1]
	s_waitcnt lgkmcnt(1)
	global_store_dwordx4 v[210:211], v[40:43], off
	s_nop 1
	v_lshl_add_u64 v[210:211], v[210:211], 0, s[0:1]
	s_waitcnt lgkmcnt(0)
	global_store_dwordx4 v[210:211], v[44:47], off
	s_branch .LBB0_408
